# v40 + attention: rescale test shortened to v_cmp_nge + s_cbranch_vccnz (one SALU op less on the serial chain after the last PV MFMA)
# speedup vs baseline: 1.0064x; 1.0013x over previous
; template <bool FIRST>
; __device__ __forceinline__ void partialSM(f32x16& p0, f32x16& p1, float& m_reg, float& alpha) {
;   float a = fmaxf(fmaxf(p0[0], p0[1]), p0[2]), b = fmaxf(fmaxf(p1[0], p1[1]), p1[2]);
; #pragma unroll
;   for (int r = 3; r < 15; r += 2) { a = fmaxf(fmaxf(a, p0[r]), p0[r + 1]); b = fmaxf(fmaxf(b, p1[r]), p1[r + 1]); }
;   float pmax = fmaxf(fmaxf(a, b), fmaxf(p0[15], p1[15]));
;   { auto rr = __builtin_amdgcn_permlane32_swap(__float_as_uint(pmax), __float_as_uint(pmax), false, false);
;     pmax = fmaxf(__uint_as_float(rr[0]), __uint_as_float(rr[1])); }
;   alpha = 1.f;
;   if (FIRST || !__builtin_expect(__all(pmax <= THRL), 1)) {
; template <int D0> __device__ __forceinline__ void pv_one(f32x16& od, int vb, bf16x8 pa0, bf16x8 pa1, bf16x8 pa2, bf16x8 pa3) {
;     ...
;   od = __builtin_amdgcn_mfma_f32_32x32x16_bf16(pa0, PKV(l0, h0), od, 0, 0, 0);
;   od = __builtin_amdgcn_mfma_f32_32x32x16_bf16(pa1, PKV(l1, h1), od, 0, 0, 0);
;   od = __builtin_amdgcn_mfma_f32_32x32x16_bf16(pa2, PKV(l2, h2), od, 0, 0, 0);
;   od = __builtin_amdgcn_mfma_f32_32x32x16_bf16(pa3, PKV(l3, h3), od, 0, 0, 0);
.Lmy_stage_1_b:
	v_mfma_f32_32x32x16_bf16 v[16:31], v[32:35], v[122:125], v[16:31]
	v_max3_f32 v32, v64, v65, v66
	v_max3_f32 v33, v48, v49, v50
	v_max3_f32 v32, v32, v67, v68
	v_max3_f32 v33, v33, v51, v52
	v_max3_f32 v32, v32, v69, v70
	v_max3_f32 v33, v33, v53, v54
	v_max3_f32 v32, v32, v71, v72
	v_mfma_f32_32x32x16_bf16 v[16:31], v[36:39], v[126:129], v[16:31]
	v_max3_f32 v33, v33, v55, v56
	v_max3_f32 v32, v32, v73, v74
	v_max3_f32 v33, v33, v57, v58
	v_max3_f32 v32, v32, v75, v76
	v_max3_f32 v33, v33, v59, v60
	v_max_f32_e32 v34, v63, v63
	v_max_f32_e32 v35, v79, v79
	v_mfma_f32_32x32x16_bf16 v[16:31], v[40:43], v[130:133], v[16:31]
	v_max3_f32 v32, v32, v77, v78
	v_max3_f32 v33, v33, v61, v62
	v_max_f32_e32 v34, v35, v34
	v_max3_f32 v32, v32, v33, v34
	v_mov_b32_e32 v33, v32
	s_nop 1
	v_permlane32_swap_b32_e32 v32, v33
	v_mfma_f32_32x32x16_bf16 v[16:31], v[44:47], v[134:137], v[16:31]
	v_max_f32_e32 v33, v33, v33
	v_max_f32_e32 v32, v32, v32
	v_max_f32_e32 v32, v32, v33
	v_cmp_nge_f32_e32 vcc, s75, v32
	s_cbranch_vccnz .LBB0_689
	v_mov_b32_e32 v159, 1.0

; template <bool FIRST>
; __device__ __forceinline__ void partialSM(f32x16& p0, f32x16& p1, float& m_reg, float& alpha) {
;   float a = fmaxf(fmaxf(p0[0], p0[1]), p0[2]), b = fmaxf(fmaxf(p1[0], p1[1]), p1[2]);
; #pragma unroll
;   for (int r = 3; r < 15; r += 2) { a = fmaxf(fmaxf(a, p0[r]), p0[r + 1]); b = fmaxf(fmaxf(b, p1[r]), p1[r + 1]); }
;   float pmax = fmaxf(fmaxf(a, b), fmaxf(p0[15], p1[15]));
;   { auto rr = __builtin_amdgcn_permlane32_swap(__float_as_uint(pmax), __float_as_uint(pmax), false, false);
;     pmax = fmaxf(__uint_as_float(rr[0]), __uint_as_float(rr[1])); }
;   alpha = 1.f;
;   if (FIRST || !__builtin_expect(__all(pmax <= THRL), 1)) {
; template <int D0> __device__ __forceinline__ void pv_one(f32x16& od, int vb, bf16x8 pa0, bf16x8 pa1, bf16x8 pa2, bf16x8 pa3) {
;     ...
;   od = __builtin_amdgcn_mfma_f32_32x32x16_bf16(pa0, PKV(l0, h0), od, 0, 0, 0);
;   od = __builtin_amdgcn_mfma_f32_32x32x16_bf16(pa1, PKV(l1, h1), od, 0, 0, 0);
;   od = __builtin_amdgcn_mfma_f32_32x32x16_bf16(pa2, PKV(l2, h2), od, 0, 0, 0);
;   od = __builtin_amdgcn_mfma_f32_32x32x16_bf16(pa3, PKV(l3, h3), od, 0, 0, 0);
.Lmy_stage_0_b:
	v_mfma_f32_32x32x16_bf16 v[16:31], v[50:53], v[126:129], v[16:31]
	v_max3_f32 v50, v64, v65, v66
	v_max3_f32 v51, v32, v33, v34
	v_max3_f32 v50, v50, v67, v68
	v_max3_f32 v51, v51, v35, v36
	v_max3_f32 v50, v50, v69, v70
	v_max3_f32 v51, v51, v37, v38
	v_max3_f32 v50, v50, v71, v72
	v_mfma_f32_32x32x16_bf16 v[16:31], v[54:57], v[130:133], v[16:31]
	v_max3_f32 v51, v51, v39, v40
	v_max3_f32 v50, v50, v73, v74
	v_max3_f32 v51, v51, v41, v42
	v_max3_f32 v50, v50, v75, v76
	v_max3_f32 v51, v51, v43, v44
	v_max_f32_e32 v52, v47, v47
	v_max_f32_e32 v53, v79, v79
	v_mfma_f32_32x32x16_bf16 v[16:31], v[58:61], v[134:137], v[16:31]
	v_max3_f32 v50, v50, v77, v78
	v_max3_f32 v51, v51, v45, v46
	v_max_f32_e32 v52, v53, v52
	v_max3_f32 v50, v50, v51, v52
	v_mov_b32_e32 v51, v50
	s_nop 1
	v_permlane32_swap_b32_e32 v50, v51
	v_mfma_f32_32x32x16_bf16 v[16:31], v[122:125], v[168:171], v[16:31]
	v_max_f32_e32 v51, v51, v51
	v_max_f32_e32 v50, v50, v50
	v_max_f32_e32 v50, v50, v51
	v_cmp_nge_f32_e32 vcc, s75, v50
	v_mov_b32_e32 v158, 1.0
	s_cbranch_vccnz .LBB0_690

; template <bool FIRST>
; __device__ __forceinline__ void partialSM(f32x16& p0, f32x16& p1, float& m_reg, float& alpha) {
;   float a = fmaxf(fmaxf(p0[0], p0[1]), p0[2]), b = fmaxf(fmaxf(p1[0], p1[1]), p1[2]);
; #pragma unroll
;   for (int r = 3; r < 15; r += 2) { a = fmaxf(fmaxf(a, p0[r]), p0[r + 1]); b = fmaxf(fmaxf(b, p1[r]), p1[r + 1]); }
;   float pmax = fmaxf(fmaxf(a, b), fmaxf(p0[15], p1[15]));
;   { auto rr = __builtin_amdgcn_permlane32_swap(__float_as_uint(pmax), __float_as_uint(pmax), false, false);
;     pmax = fmaxf(__uint_as_float(rr[0]), __uint_as_float(rr[1])); }
;   alpha = 1.f;
;   if (FIRST || !__builtin_expect(__all(pmax <= THRL), 1)) {
; template <int D0> __device__ __forceinline__ void pv_one(f32x16& od, int vb, bf16x8 pa0, bf16x8 pa1, bf16x8 pa2, bf16x8 pa3) {
;     ...
;   od = __builtin_amdgcn_mfma_f32_32x32x16_bf16(pa0, PKV(l0, h0), od, 0, 0, 0);
;   od = __builtin_amdgcn_mfma_f32_32x32x16_bf16(pa1, PKV(l1, h1), od, 0, 0, 0);
;   od = __builtin_amdgcn_mfma_f32_32x32x16_bf16(pa2, PKV(l2, h2), od, 0, 0, 0);
;   od = __builtin_amdgcn_mfma_f32_32x32x16_bf16(pa3, PKV(l3, h3), od, 0, 0, 0);
.Lmy_stage_3_b:
	v_mfma_f32_32x32x16_bf16 v[16:31], v[32:35], v[122:125], v[16:31]
	v_max3_f32 v32, v64, v65, v66
	v_max3_f32 v33, v48, v49, v50
	v_max3_f32 v32, v32, v67, v68
	v_max3_f32 v33, v33, v51, v52
	v_max3_f32 v32, v32, v69, v70
	v_max3_f32 v33, v33, v53, v54
	v_max3_f32 v32, v32, v71, v72
	v_mfma_f32_32x32x16_bf16 v[16:31], v[36:39], v[126:129], v[16:31]
	v_max3_f32 v33, v33, v55, v56
	v_max3_f32 v32, v32, v73, v74
	v_max3_f32 v33, v33, v57, v58
	v_max3_f32 v32, v32, v75, v76
	v_max3_f32 v33, v33, v59, v60
	v_max_f32_e32 v34, v63, v63
	v_max_f32_e32 v35, v79, v79
	v_mfma_f32_32x32x16_bf16 v[16:31], v[40:43], v[130:133], v[16:31]
	v_max3_f32 v32, v32, v77, v78
	v_max3_f32 v33, v33, v61, v62
	v_max_f32_e32 v34, v35, v34
	v_max3_f32 v32, v32, v33, v34
	v_mov_b32_e32 v33, v32
	s_nop 1
	v_permlane32_swap_b32_e32 v32, v33
	v_mfma_f32_32x32x16_bf16 v[16:31], v[44:47], v[134:137], v[16:31]
	v_max_f32_e32 v33, v33, v33
	v_max_f32_e32 v32, v32, v32
	v_max_f32_e32 v32, v32, v33
	v_cmp_nge_f32_e32 vcc, s78, v32
	s_cbranch_vccnz .LBB0_736
	v_mov_b32_e32 v159, 1.0

; template <bool FIRST>
; __device__ __forceinline__ void partialSM(f32x16& p0, f32x16& p1, float& m_reg, float& alpha) {
;   float a = fmaxf(fmaxf(p0[0], p0[1]), p0[2]), b = fmaxf(fmaxf(p1[0], p1[1]), p1[2]);
; #pragma unroll
;   for (int r = 3; r < 15; r += 2) { a = fmaxf(fmaxf(a, p0[r]), p0[r + 1]); b = fmaxf(fmaxf(b, p1[r]), p1[r + 1]); }
;   float pmax = fmaxf(fmaxf(a, b), fmaxf(p0[15], p1[15]));
;   { auto rr = __builtin_amdgcn_permlane32_swap(__float_as_uint(pmax), __float_as_uint(pmax), false, false);
;     pmax = fmaxf(__uint_as_float(rr[0]), __uint_as_float(rr[1])); }
;   alpha = 1.f;
;   if (FIRST || !__builtin_expect(__all(pmax <= THRL), 1)) {
; template <int D0> __device__ __forceinline__ void pv_one(f32x16& od, int vb, bf16x8 pa0, bf16x8 pa1, bf16x8 pa2, bf16x8 pa3) {
;     ...
;   od = __builtin_amdgcn_mfma_f32_32x32x16_bf16(pa0, PKV(l0, h0), od, 0, 0, 0);
;   od = __builtin_amdgcn_mfma_f32_32x32x16_bf16(pa1, PKV(l1, h1), od, 0, 0, 0);
;   od = __builtin_amdgcn_mfma_f32_32x32x16_bf16(pa2, PKV(l2, h2), od, 0, 0, 0);
;   od = __builtin_amdgcn_mfma_f32_32x32x16_bf16(pa3, PKV(l3, h3), od, 0, 0, 0);
.Lmy_stage_2_b:
	v_mfma_f32_32x32x16_bf16 v[16:31], v[50:53], v[126:129], v[16:31]
	v_max3_f32 v50, v64, v65, v66
	v_max3_f32 v51, v32, v33, v34
	v_max3_f32 v50, v50, v67, v68
	v_max3_f32 v51, v51, v35, v36
	v_max3_f32 v50, v50, v69, v70
	v_max3_f32 v51, v51, v37, v38
	v_max3_f32 v50, v50, v71, v72
	v_mfma_f32_32x32x16_bf16 v[16:31], v[54:57], v[130:133], v[16:31]
	v_max3_f32 v51, v51, v39, v40
	v_max3_f32 v50, v50, v73, v74
	v_max3_f32 v51, v51, v41, v42
	v_max3_f32 v50, v50, v75, v76
	v_max3_f32 v51, v51, v43, v44
	v_max_f32_e32 v52, v47, v47
	v_max_f32_e32 v53, v79, v79
	v_mfma_f32_32x32x16_bf16 v[16:31], v[58:61], v[134:137], v[16:31]
	v_max3_f32 v50, v50, v77, v78
	v_max3_f32 v51, v51, v45, v46
	v_max_f32_e32 v52, v53, v52
	v_max3_f32 v50, v50, v51, v52
	v_mov_b32_e32 v51, v50
	s_nop 1
	v_permlane32_swap_b32_e32 v50, v51
	v_mfma_f32_32x32x16_bf16 v[16:31], v[122:125], v[168:171], v[16:31]
	v_max_f32_e32 v51, v51, v51
	v_max_f32_e32 v50, v50, v50
	v_max_f32_e32 v50, v50, v51
	v_cmp_nge_f32_e32 vcc, s78, v50
	v_mov_b32_e32 v158, 1.0
	s_cbranch_vccnz .LBB0_737
